# norm_phase hand-written (both sites): streaming, params hoisted, all loads of a 4-row iteration in flight, scalar addressing
# speedup vs baseline: 1.0217x; 1.0217x over previous
; DI int otid() { int t = threadIdx.x & 255; asm volatile("" : "+v"(t)); return t; }
; DI int oidx(int i) { asm volatile("" : "+s"(i)); return i; }
; DN void norm_phase(const Params& p, int l, int which, bool from_input, bool skip_ctx) {
;   const int tid = otid(), lane = tid & 63;
;   const int wave = (VB() * 256 + tid) >> 6, nw = NVB() * 4;
;   const float* g = p.in[oidx(6) + which] + l * DM;
;   const float* MOD = (const float*)(p.ws + OFF_MOD);
;   bfr* H = (bfr*)(p.ws + OFF_HO);
;   for (int m0 = wave * 4; m0 < MR; m0 += nw * 4) {
;     f32x4v v[4][4];
;     float ss[4];
;     bool act[4];
;     const float* modp[4];
; #pragma unroll
;     for (int q = 0; q < 4; ++q) {
;       const int m = m0 + q;
;       const int b = m / TT, t = m - b * TT;
;       const bool isctx = t >= TL;
;       act[q] = !(isctx && skip_ctx);
;       const float* src = from_input ? in_row(p, b, t) : res_row(p, b, t);
;       modp[q] = MOD + (size_t)(l * 17 + (isctx ? 16 : b)) * 6144;
;       ss[q] = 0.f;
;       if (act[q]) {
; #pragma unroll
;         for (int i = 0; i < 4; ++i) {
;           v[q][i] = *(const f32x4v*)(src + i * 256 + lane * 4);
;           ss[q] += v[q][i].x * v[q][i].x + v[q][i].y * v[q][i].y + v[q][i].z * v[q][i].z + v[q][i].w * v[q][i].w;
;         }
;       } else {
; #pragma unroll
;         for (int i = 0; i < 4; ++i) v[q][i] = (f32x4v){0.f, 0.f, 0.f, 0.f};
;       }
;     }
; #pragma unroll
;     for (int q = 0; q < 4; ++q) {
;       if (!act[q]) continue;
;       const int m = m0 + q;
;       const float* shift = modp[q] + (which ? 3 : 0) * DM;
;       const float* scale = modp[q] + (which ? 4 : 1) * DM;
;       const float tot = wave_sum(ss[q]);
;       const float rstd = rsqrtf(tot * (1.f / DM) + 1e-6f);
; #pragma unroll
;       for (int i = 0; i < 4; ++i) {
;         const int k = i * 256 + lane * 4;
;         const f32x4v gg = *(const f32x4v*)(g + k), sc = *(const f32x4v*)(scale + k), sh = *(const f32x4v*)(shift + k);
;         const float o0 = (v[q][i].x * rstd * gg.x) * (1.f + sc.x) + sh.x;
;         const float o1 = (v[q][i].y * rstd * gg.y) * (1.f + sc.y) + sh.y;
;         const float o2 = (v[q][i].z * rstd * gg.z) * (1.f + sc.z) + sh.z;
;         const float o3 = (v[q][i].w * rstd * gg.w) * (1.f + sc.w) + sh.w;
;         uint2 pk; pk.x = pack2(o0, o1); pk.y = pack2(o2, o3);
;         *(uint2*)(H + (size_t)m * DM + k) = pk;
.LBB0_154:
	s_xor_b64 s[2:3], s[92:93], -1
	v_writelane_b32 v253, s2, 22
	v_mov_b32_e32 v0, v183
	s_nop 0
	v_writelane_b32 v253, s3, 23
	v_readlane_b32 s3, v252, 2
	v_readlane_b32 s2, v253, 13
	s_mul_i32 s2, s2, 17
	s_nop 0
	v_writelane_b32 v253, s2, 24
	v_readlane_b32 s2, v253, 13
	v_readlane_b32 s3, v252, 0
	v_readfirstlane_b32 s14, v182
	s_lshr_b32 s14, s14, 6
	s_lshl_b32 s3, s3, 3
	s_add_i32 s3, s3, s14
	s_lshl_b32 s3, s3, 2
	s_load_dwordx2 s[8:9], s[0:1], 0x30
	s_load_dwordx2 s[4:5], s[0:1], 0x108
	v_and_b32_e32 v112, 63, v182
	v_lshlrev_b32_e32 v116, 3, v112
	v_lshlrev_b32_e32 v112, 4, v112
	v_add_u32_e32 v113, 0x1000, v112
	v_add_u32_e32 v117, 0x800, v116
	v_add_u32_e32 v114, 0x2000, v112
	v_add_u32_e32 v118, 0x1000, v116
	v_add_u32_e32 v115, 0x3000, v112
	v_add_u32_e32 v119, 0x1800, v116
	s_lshl_b32 s14, s2, 12
	s_waitcnt lgkmcnt(0)
	s_add_u32 s8, s8, s14
	s_addc_u32 s9, s9, 0
	global_load_dwordx4 v[0:3], v112, s[8:9]
	global_load_dwordx4 v[4:7], v112, s[8:9] offset:1024
	global_load_dwordx4 v[8:11], v112, s[8:9] offset:2048
	global_load_dwordx4 v[12:15], v112, s[8:9] offset:3072
.Lnrma_iter:
	s_mul_i32 s14, s3, 0xe39
	s_lshr_b32 s14, s14, 23
	s_mul_i32 s15, s14, 0x900
	s_sub_i32 s15, s3, s15
	s_cmpk_ge_i32 s15, 0x800
	s_cselect_b32 s98, 16, s14
	s_mul_i32 s99, s2, 17
	s_add_i32 s98, s98, s99
	s_mul_i32 s98, s98, 0x6000
	s_add_u32 s10, s4, 0x19f0000
	s_addc_u32 s11, s5, 0
	s_add_u32 s10, s10, s98
	s_addc_u32 s11, s11, 0
	s_add_u32 s12, s10, 0x1000
	s_addc_u32 s13, s11, 0
	global_load_dwordx4 v[32:35], v112, s[10:11]
	global_load_dwordx4 v[36:39], v112, s[10:11] offset:1024
	global_load_dwordx4 v[40:43], v112, s[10:11] offset:2048
	global_load_dwordx4 v[44:47], v112, s[10:11] offset:3072
	global_load_dwordx4 v[16:19], v112, s[12:13]
	global_load_dwordx4 v[20:23], v112, s[12:13] offset:1024
	global_load_dwordx4 v[24:27], v112, s[12:13] offset:2048
	global_load_dwordx4 v[28:31], v112, s[12:13] offset:3072
	s_cmpk_ge_i32 s15, 0x800
	s_movk_i32 s98, 0x100
	s_cselect_b32 s98, 0x108, s98
	s_cselect_b32 s99, 0x10, 0x0
	s_cmp_eq_u32 s2, 0
	s_cselect_b32 s98, s99, s98
	s_cmpk_ge_i32 s15, 0x800
	s_load_dwordx2 s[8:9], s[0:1], s98
	s_lshl_b32 s99, s14, 11
	s_add_i32 s99, s99, s15
	s_lshl_b32 s14, s14, 8
	s_add_i32 s14, s14, s15
	s_addk_i32 s14, 0xf800
	s_cmpk_ge_i32 s15, 0x800
	s_cselect_b32 s99, s14, s99
	s_cselect_b32 s14, 0x1abc000, 0
	s_cmp_eq_u32 s2, 0
	s_cselect_b32 s14, 0, s14
	s_lshl_b32 s15, s99, 12
	s_waitcnt lgkmcnt(0)
	s_add_u32 s8, s8, s14
	s_addc_u32 s9, s9, 0
	s_add_u32 s8, s8, s15
	s_addc_u32 s9, s9, 0
	global_load_dwordx4 v[48:51], v112, s[8:9]
	global_load_dwordx4 v[52:55], v112, s[8:9] offset:1024
	global_load_dwordx4 v[56:59], v112, s[8:9] offset:2048
	global_load_dwordx4 v[60:63], v112, s[8:9] offset:3072
	global_load_dwordx4 v[64:67], v113, s[8:9]
	global_load_dwordx4 v[68:71], v113, s[8:9] offset:1024
	global_load_dwordx4 v[72:75], v113, s[8:9] offset:2048
	global_load_dwordx4 v[76:79], v113, s[8:9] offset:3072
	global_load_dwordx4 v[80:83], v114, s[8:9]
	global_load_dwordx4 v[84:87], v114, s[8:9] offset:1024
	global_load_dwordx4 v[88:91], v114, s[8:9] offset:2048
	global_load_dwordx4 v[92:95], v114, s[8:9] offset:3072
	global_load_dwordx4 v[96:99], v115, s[8:9]
	global_load_dwordx4 v[100:103], v115, s[8:9] offset:1024
	global_load_dwordx4 v[104:107], v115, s[8:9] offset:2048
	global_load_dwordx4 v[108:111], v115, s[8:9] offset:3072
	s_lshl_b32 s14, s3, 11
	s_add_u32 s10, s4, 0x2b7c100
	s_addc_u32 s11, s5, 0
	s_add_u32 s10, s10, s14
	s_addc_u32 s11, s11, 0
	s_waitcnt vmcnt(16)
	v_add_f32_e32 v16, 1.0, v16
	v_add_f32_e32 v17, 1.0, v17
	v_add_f32_e32 v18, 1.0, v18
	v_add_f32_e32 v19, 1.0, v19
	v_add_f32_e32 v20, 1.0, v20
	v_add_f32_e32 v21, 1.0, v21
	v_add_f32_e32 v22, 1.0, v22
	v_add_f32_e32 v23, 1.0, v23
	v_add_f32_e32 v24, 1.0, v24
	v_add_f32_e32 v25, 1.0, v25
	v_add_f32_e32 v26, 1.0, v26
	v_add_f32_e32 v27, 1.0, v27
	v_add_f32_e32 v28, 1.0, v28
	v_add_f32_e32 v29, 1.0, v29
	v_add_f32_e32 v30, 1.0, v30
	v_add_f32_e32 v31, 1.0, v31
	s_waitcnt vmcnt(12)
	v_mul_f32_e32 v120, v48, v48
	v_fmac_f32_e32 v120, v49, v49
	v_fmac_f32_e32 v120, v50, v50
	v_fmac_f32_e32 v120, v51, v51
	v_fmac_f32_e32 v120, v52, v52
	v_fmac_f32_e32 v120, v53, v53
	v_fmac_f32_e32 v120, v54, v54
	v_fmac_f32_e32 v120, v55, v55
	v_fmac_f32_e32 v120, v56, v56
	v_fmac_f32_e32 v120, v57, v57
	v_fmac_f32_e32 v120, v58, v58
	v_fmac_f32_e32 v120, v59, v59
	v_fmac_f32_e32 v120, v60, v60
	v_fmac_f32_e32 v120, v61, v61
	v_fmac_f32_e32 v120, v62, v62
	v_fmac_f32_e32 v120, v63, v63
	s_nop 1
	v_add_f32_dpp v120, v120, v120 quad_perm:[1,0,3,2] row_mask:0xf bank_mask:0xf bound_ctrl:1
	s_nop 1
	v_add_f32_dpp v120, v120, v120 quad_perm:[2,3,0,1] row_mask:0xf bank_mask:0xf bound_ctrl:1
	s_nop 1
	v_add_f32_dpp v120, v120, v120 row_half_mirror row_mask:0xf bank_mask:0xf bound_ctrl:1
	s_nop 1
	v_add_f32_dpp v120, v120, v120 row_mirror row_mask:0xf bank_mask:0xf bound_ctrl:1
	s_nop 1
	v_readlane_b32 s14, v120, 0
	v_readlane_b32 s15, v120, 16
	v_readlane_b32 s98, v120, 32
	v_readlane_b32 s99, v120, 48
	s_nop 1
	v_mov_b32_e32 v124, s14
	v_mov_b32_e32 v125, s98
	v_add_f32_e32 v124, s15, v124
	v_add_f32_e32 v125, s99, v125
	v_add_f32_e32 v124, v124, v125
	v_mul_f32_e32 v124, 0x3a800000, v124
	v_add_f32_e32 v124, 0x358637bd, v124
	v_rsq_f32_e32 v124, v124
	s_nop 0
	v_mul_f32_e32 v48, v48, v124
	v_mul_f32_e32 v49, v49, v124
	v_mul_f32_e32 v50, v50, v124
	v_mul_f32_e32 v51, v51, v124
	v_mul_f32_e32 v48, v48, v0
	v_mul_f32_e32 v49, v49, v1
	v_mul_f32_e32 v50, v50, v2
	v_mul_f32_e32 v51, v51, v3
	v_fma_f32 v48, v48, v16, v32
	v_fma_f32 v49, v49, v17, v33
	v_fma_f32 v50, v50, v18, v34
; DI unsigned pack2(float a, float b) { unsigned r; asm volatile("v_cvt_pk_bf16_f32 %0, %1, %2" : "=v"(r) : "v"(a), "v"(b)); return r; }
; DN void norm_phase(const Params& p, int l, int which, bool from_input, bool skip_ctx) {
;     ...
; #pragma unroll
;     for (int q = 0; q < 4; ++q) {
;       if (!act[q]) continue;
;       const int m = m0 + q;
;       const float* shift = modp[q] + (which ? 3 : 0) * DM;
;       const float* scale = modp[q] + (which ? 4 : 1) * DM;
;       const float tot = wave_sum(ss[q]);
;       const float rstd = rsqrtf(tot * (1.f / DM) + 1e-6f);
; #pragma unroll
;       for (int i = 0; i < 4; ++i) {
;         const int k = i * 256 + lane * 4;
;         const f32x4v gg = *(const f32x4v*)(g + k), sc = *(const f32x4v*)(scale + k), sh = *(const f32x4v*)(shift + k);
;         const float o0 = (v[q][i].x * rstd * gg.x) * (1.f + sc.x) + sh.x;
;         const float o1 = (v[q][i].y * rstd * gg.y) * (1.f + sc.y) + sh.y;
;         const float o2 = (v[q][i].z * rstd * gg.z) * (1.f + sc.z) + sh.z;
;         const float o3 = (v[q][i].w * rstd * gg.w) * (1.f + sc.w) + sh.w;
;         uint2 pk; pk.x = pack2(o0, o1); pk.y = pack2(o2, o3);
;         *(uint2*)(H + (size_t)m * DM + k) = pk;
;       }
	v_fma_f32 v51, v51, v19, v35
	v_cvt_pk_bf16_f32 v128, v48, v49
	v_cvt_pk_bf16_f32 v129, v50, v51
	v_mul_f32_e32 v52, v52, v124
	v_mul_f32_e32 v53, v53, v124
	v_mul_f32_e32 v54, v54, v124
	v_mul_f32_e32 v55, v55, v124
	v_mul_f32_e32 v52, v52, v4
	v_mul_f32_e32 v53, v53, v5
	v_mul_f32_e32 v54, v54, v6
	v_mul_f32_e32 v55, v55, v7
	v_fma_f32 v52, v52, v20, v36
	v_fma_f32 v53, v53, v21, v37
	v_fma_f32 v54, v54, v22, v38
	v_fma_f32 v55, v55, v23, v39
	v_cvt_pk_bf16_f32 v130, v52, v53
	v_cvt_pk_bf16_f32 v131, v54, v55
	v_mul_f32_e32 v56, v56, v124
	v_mul_f32_e32 v57, v57, v124
	v_mul_f32_e32 v58, v58, v124
	v_mul_f32_e32 v59, v59, v124
	v_mul_f32_e32 v56, v56, v8
	v_mul_f32_e32 v57, v57, v9
	v_mul_f32_e32 v58, v58, v10
	v_mul_f32_e32 v59, v59, v11
	v_fma_f32 v56, v56, v24, v40
	v_fma_f32 v57, v57, v25, v41
	v_fma_f32 v58, v58, v26, v42
	v_fma_f32 v59, v59, v27, v43
	v_cvt_pk_bf16_f32 v132, v56, v57
	v_cvt_pk_bf16_f32 v133, v58, v59
	v_mul_f32_e32 v60, v60, v124
	v_mul_f32_e32 v61, v61, v124
	v_mul_f32_e32 v62, v62, v124
	v_mul_f32_e32 v63, v63, v124
	v_mul_f32_e32 v60, v60, v12
	v_mul_f32_e32 v61, v61, v13
	v_mul_f32_e32 v62, v62, v14
	v_mul_f32_e32 v63, v63, v15
	v_fma_f32 v60, v60, v28, v44
	v_fma_f32 v61, v61, v29, v45
	v_fma_f32 v62, v62, v30, v46
	v_fma_f32 v63, v63, v31, v47
	v_cvt_pk_bf16_f32 v134, v60, v61
	v_cvt_pk_bf16_f32 v135, v62, v63
	global_store_dwordx2 v116, v[128:129], s[10:11]
	global_store_dwordx2 v116, v[130:131], s[10:11] offset:512
	global_store_dwordx2 v116, v[132:133], s[10:11] offset:1024
	global_store_dwordx2 v116, v[134:135], s[10:11] offset:1536
	s_waitcnt vmcnt(12)
	v_mul_f32_e32 v121, v64, v64
	v_fmac_f32_e32 v121, v65, v65
	v_fmac_f32_e32 v121, v66, v66
	v_fmac_f32_e32 v121, v67, v67
	v_fmac_f32_e32 v121, v68, v68
	v_fmac_f32_e32 v121, v69, v69
	v_fmac_f32_e32 v121, v70, v70
	v_fmac_f32_e32 v121, v71, v71
	v_fmac_f32_e32 v121, v72, v72
	v_fmac_f32_e32 v121, v73, v73
	v_fmac_f32_e32 v121, v74, v74
	v_fmac_f32_e32 v121, v75, v75
	v_fmac_f32_e32 v121, v76, v76
	v_fmac_f32_e32 v121, v77, v77
	v_fmac_f32_e32 v121, v78, v78
	v_fmac_f32_e32 v121, v79, v79
	s_nop 1
	v_add_f32_dpp v121, v121, v121 quad_perm:[1,0,3,2] row_mask:0xf bank_mask:0xf bound_ctrl:1
	s_nop 1
	v_add_f32_dpp v121, v121, v121 quad_perm:[2,3,0,1] row_mask:0xf bank_mask:0xf bound_ctrl:1
	s_nop 1
	v_add_f32_dpp v121, v121, v121 row_half_mirror row_mask:0xf bank_mask:0xf bound_ctrl:1
	s_nop 1
	v_add_f32_dpp v121, v121, v121 row_mirror row_mask:0xf bank_mask:0xf bound_ctrl:1
	s_nop 1
	v_readlane_b32 s14, v121, 0
	v_readlane_b32 s15, v121, 16
	v_readlane_b32 s98, v121, 32
	v_readlane_b32 s99, v121, 48
	s_nop 1
	v_mov_b32_e32 v124, s14
	v_mov_b32_e32 v125, s98
	v_add_f32_e32 v124, s15, v124
	v_add_f32_e32 v125, s99, v125
	v_add_f32_e32 v124, v124, v125
	v_mul_f32_e32 v124, 0x3a800000, v124
	v_add_f32_e32 v124, 0x358637bd, v124
	v_rsq_f32_e32 v124, v124
	s_nop 0
	v_mul_f32_e32 v64, v64, v124
	v_mul_f32_e32 v65, v65, v124
	v_mul_f32_e32 v66, v66, v124
	v_mul_f32_e32 v67, v67, v124
	v_mul_f32_e32 v64, v64, v0
	v_mul_f32_e32 v65, v65, v1
	v_mul_f32_e32 v66, v66, v2
	v_mul_f32_e32 v67, v67, v3
	v_fma_f32 v64, v64, v16, v32
	v_fma_f32 v65, v65, v17, v33
	v_fma_f32 v66, v66, v18, v34
	v_fma_f32 v67, v67, v19, v35
	v_cvt_pk_bf16_f32 v128, v64, v65
	v_cvt_pk_bf16_f32 v129, v66, v67
	v_mul_f32_e32 v68, v68, v124
	v_mul_f32_e32 v69, v69, v124
	v_mul_f32_e32 v70, v70, v124
	v_mul_f32_e32 v71, v71, v124
	v_mul_f32_e32 v68, v68, v4
	v_mul_f32_e32 v69, v69, v5
	v_mul_f32_e32 v70, v70, v6
	v_mul_f32_e32 v71, v71, v7
	v_fma_f32 v68, v68, v20, v36
	v_fma_f32 v69, v69, v21, v37
	v_fma_f32 v70, v70, v22, v38
	v_fma_f32 v71, v71, v23, v39
	v_cvt_pk_bf16_f32 v130, v68, v69
	v_cvt_pk_bf16_f32 v131, v70, v71
	v_mul_f32_e32 v72, v72, v124
	v_mul_f32_e32 v73, v73, v124
	v_mul_f32_e32 v74, v74, v124
	v_mul_f32_e32 v75, v75, v124
	v_mul_f32_e32 v72, v72, v8
	v_mul_f32_e32 v73, v73, v9
	v_mul_f32_e32 v74, v74, v10
	v_mul_f32_e32 v75, v75, v11
	v_fma_f32 v72, v72, v24, v40
	v_fma_f32 v73, v73, v25, v41
	v_fma_f32 v74, v74, v26, v42
	v_fma_f32 v75, v75, v27, v43
	v_cvt_pk_bf16_f32 v132, v72, v73
	v_cvt_pk_bf16_f32 v133, v74, v75
	v_mul_f32_e32 v76, v76, v124
	v_mul_f32_e32 v77, v77, v124
	v_mul_f32_e32 v78, v78, v124
	v_mul_f32_e32 v79, v79, v124
	v_mul_f32_e32 v76, v76, v12
	v_mul_f32_e32 v77, v77, v13
	v_mul_f32_e32 v78, v78, v14
	v_mul_f32_e32 v79, v79, v15
	v_fma_f32 v76, v76, v28, v44
	v_fma_f32 v77, v77, v29, v45
	v_fma_f32 v78, v78, v30, v46
	v_fma_f32 v79, v79, v31, v47
	v_cvt_pk_bf16_f32 v134, v76, v77
	v_cvt_pk_bf16_f32 v135, v78, v79
	global_store_dwordx2 v117, v[128:129], s[10:11]
	global_store_dwordx2 v117, v[130:131], s[10:11] offset:512
	global_store_dwordx2 v117, v[132:133], s[10:11] offset:1024
	global_store_dwordx2 v117, v[134:135], s[10:11] offset:1536
	s_waitcnt vmcnt(12)
; DI unsigned pack2(float a, float b) { unsigned r; asm volatile("v_cvt_pk_bf16_f32 %0, %1, %2" : "=v"(r) : "v"(a), "v"(b)); return r; }
; DN void norm_phase(const Params& p, int l, int which, bool from_input, bool skip_ctx) {
;     ...
; #pragma unroll
;     for (int q = 0; q < 4; ++q) {
;       if (!act[q]) continue;
;       const int m = m0 + q;
;       const float* shift = modp[q] + (which ? 3 : 0) * DM;
;       const float* scale = modp[q] + (which ? 4 : 1) * DM;
;       const float tot = wave_sum(ss[q]);
;       const float rstd = rsqrtf(tot * (1.f / DM) + 1e-6f);
; #pragma unroll
;       for (int i = 0; i < 4; ++i) {
;         const int k = i * 256 + lane * 4;
;         const f32x4v gg = *(const f32x4v*)(g + k), sc = *(const f32x4v*)(scale + k), sh = *(const f32x4v*)(shift + k);
;         const float o0 = (v[q][i].x * rstd * gg.x) * (1.f + sc.x) + sh.x;
;         const float o1 = (v[q][i].y * rstd * gg.y) * (1.f + sc.y) + sh.y;
;         const float o2 = (v[q][i].z * rstd * gg.z) * (1.f + sc.z) + sh.z;
;         const float o3 = (v[q][i].w * rstd * gg.w) * (1.f + sc.w) + sh.w;
;         uint2 pk; pk.x = pack2(o0, o1); pk.y = pack2(o2, o3);
;         *(uint2*)(H + (size_t)m * DM + k) = pk;
;       }
;     }
;   }
	v_mul_f32_e32 v122, v80, v80
	v_fmac_f32_e32 v122, v81, v81
	v_fmac_f32_e32 v122, v82, v82
	v_fmac_f32_e32 v122, v83, v83
	v_fmac_f32_e32 v122, v84, v84
	v_fmac_f32_e32 v122, v85, v85
	v_fmac_f32_e32 v122, v86, v86
	v_fmac_f32_e32 v122, v87, v87
	v_fmac_f32_e32 v122, v88, v88
	v_fmac_f32_e32 v122, v89, v89
	v_fmac_f32_e32 v122, v90, v90
	v_fmac_f32_e32 v122, v91, v91
	v_fmac_f32_e32 v122, v92, v92
	v_fmac_f32_e32 v122, v93, v93
	v_fmac_f32_e32 v122, v94, v94
	v_fmac_f32_e32 v122, v95, v95
	s_nop 1
	v_add_f32_dpp v122, v122, v122 quad_perm:[1,0,3,2] row_mask:0xf bank_mask:0xf bound_ctrl:1
	s_nop 1
	v_add_f32_dpp v122, v122, v122 quad_perm:[2,3,0,1] row_mask:0xf bank_mask:0xf bound_ctrl:1
	s_nop 1
	v_add_f32_dpp v122, v122, v122 row_half_mirror row_mask:0xf bank_mask:0xf bound_ctrl:1
	s_nop 1
	v_add_f32_dpp v122, v122, v122 row_mirror row_mask:0xf bank_mask:0xf bound_ctrl:1
	s_nop 1
	v_readlane_b32 s14, v122, 0
	v_readlane_b32 s15, v122, 16
	v_readlane_b32 s98, v122, 32
	v_readlane_b32 s99, v122, 48
	s_nop 1
	v_mov_b32_e32 v124, s14
	v_mov_b32_e32 v125, s98
	v_add_f32_e32 v124, s15, v124
	v_add_f32_e32 v125, s99, v125
	v_add_f32_e32 v124, v124, v125
	v_mul_f32_e32 v124, 0x3a800000, v124
	v_add_f32_e32 v124, 0x358637bd, v124
	v_rsq_f32_e32 v124, v124
	s_nop 0
	v_mul_f32_e32 v80, v80, v124
	v_mul_f32_e32 v81, v81, v124
	v_mul_f32_e32 v82, v82, v124
	v_mul_f32_e32 v83, v83, v124
	v_mul_f32_e32 v80, v80, v0
	v_mul_f32_e32 v81, v81, v1
	v_mul_f32_e32 v82, v82, v2
	v_mul_f32_e32 v83, v83, v3
	v_fma_f32 v80, v80, v16, v32
	v_fma_f32 v81, v81, v17, v33
	v_fma_f32 v82, v82, v18, v34
	v_fma_f32 v83, v83, v19, v35
	v_cvt_pk_bf16_f32 v128, v80, v81
	v_cvt_pk_bf16_f32 v129, v82, v83
	v_mul_f32_e32 v84, v84, v124
	v_mul_f32_e32 v85, v85, v124
	v_mul_f32_e32 v86, v86, v124
	v_mul_f32_e32 v87, v87, v124
	v_mul_f32_e32 v84, v84, v4
	v_mul_f32_e32 v85, v85, v5
	v_mul_f32_e32 v86, v86, v6
	v_mul_f32_e32 v87, v87, v7
	v_fma_f32 v84, v84, v20, v36
	v_fma_f32 v85, v85, v21, v37
	v_fma_f32 v86, v86, v22, v38
	v_fma_f32 v87, v87, v23, v39
	v_cvt_pk_bf16_f32 v130, v84, v85
	v_cvt_pk_bf16_f32 v131, v86, v87
	v_mul_f32_e32 v88, v88, v124
	v_mul_f32_e32 v89, v89, v124
	v_mul_f32_e32 v90, v90, v124
	v_mul_f32_e32 v91, v91, v124
	v_mul_f32_e32 v88, v88, v8
	v_mul_f32_e32 v89, v89, v9
	v_mul_f32_e32 v90, v90, v10
	v_mul_f32_e32 v91, v91, v11
	v_fma_f32 v88, v88, v24, v40
	v_fma_f32 v89, v89, v25, v41
	v_fma_f32 v90, v90, v26, v42
	v_fma_f32 v91, v91, v27, v43
	v_cvt_pk_bf16_f32 v132, v88, v89
	v_cvt_pk_bf16_f32 v133, v90, v91
	v_mul_f32_e32 v92, v92, v124
	v_mul_f32_e32 v93, v93, v124
	v_mul_f32_e32 v94, v94, v124
	v_mul_f32_e32 v95, v95, v124
	v_mul_f32_e32 v92, v92, v12
	v_mul_f32_e32 v93, v93, v13
	v_mul_f32_e32 v94, v94, v14
	v_mul_f32_e32 v95, v95, v15
	v_fma_f32 v92, v92, v28, v44
	v_fma_f32 v93, v93, v29, v45
	v_fma_f32 v94, v94, v30, v46
	v_fma_f32 v95, v95, v31, v47
	v_cvt_pk_bf16_f32 v134, v92, v93
	v_cvt_pk_bf16_f32 v135, v94, v95
	global_store_dwordx2 v118, v[128:129], s[10:11]
	global_store_dwordx2 v118, v[130:131], s[10:11] offset:512
	global_store_dwordx2 v118, v[132:133], s[10:11] offset:1024
	global_store_dwordx2 v118, v[134:135], s[10:11] offset:1536
	s_waitcnt vmcnt(12)
	v_mul_f32_e32 v123, v96, v96
	v_fmac_f32_e32 v123, v97, v97
	v_fmac_f32_e32 v123, v98, v98
	v_fmac_f32_e32 v123, v99, v99
	v_fmac_f32_e32 v123, v100, v100
	v_fmac_f32_e32 v123, v101, v101
	v_fmac_f32_e32 v123, v102, v102
	v_fmac_f32_e32 v123, v103, v103
	v_fmac_f32_e32 v123, v104, v104
	v_fmac_f32_e32 v123, v105, v105
	v_fmac_f32_e32 v123, v106, v106
	v_fmac_f32_e32 v123, v107, v107
	v_fmac_f32_e32 v123, v108, v108
	v_fmac_f32_e32 v123, v109, v109
	v_fmac_f32_e32 v123, v110, v110
	v_fmac_f32_e32 v123, v111, v111
	s_nop 1
	v_add_f32_dpp v123, v123, v123 quad_perm:[1,0,3,2] row_mask:0xf bank_mask:0xf bound_ctrl:1
	s_nop 1
	v_add_f32_dpp v123, v123, v123 quad_perm:[2,3,0,1] row_mask:0xf bank_mask:0xf bound_ctrl:1
	s_nop 1
	v_add_f32_dpp v123, v123, v123 row_half_mirror row_mask:0xf bank_mask:0xf bound_ctrl:1
	s_nop 1
	v_add_f32_dpp v123, v123, v123 row_mirror row_mask:0xf bank_mask:0xf bound_ctrl:1
	s_nop 1
	v_readlane_b32 s14, v123, 0
	v_readlane_b32 s15, v123, 16
	v_readlane_b32 s98, v123, 32
	v_readlane_b32 s99, v123, 48
	s_nop 1
	v_mov_b32_e32 v124, s14
	v_mov_b32_e32 v125, s98
	v_add_f32_e32 v124, s15, v124
	v_add_f32_e32 v125, s99, v125
	v_add_f32_e32 v124, v124, v125
	v_mul_f32_e32 v124, 0x3a800000, v124
	v_add_f32_e32 v124, 0x358637bd, v124
	v_rsq_f32_e32 v124, v124
	s_nop 0
	v_mul_f32_e32 v96, v96, v124
	v_mul_f32_e32 v97, v97, v124
	v_mul_f32_e32 v98, v98, v124
	v_mul_f32_e32 v99, v99, v124
	v_mul_f32_e32 v96, v96, v0
	v_mul_f32_e32 v97, v97, v1
	v_mul_f32_e32 v98, v98, v2
	v_mul_f32_e32 v99, v99, v3
	v_fma_f32 v96, v96, v16, v32
	v_fma_f32 v97, v97, v17, v33
	v_fma_f32 v98, v98, v18, v34
	v_fma_f32 v99, v99, v19, v35
	v_cvt_pk_bf16_f32 v128, v96, v97
	v_cvt_pk_bf16_f32 v129, v98, v99
	v_mul_f32_e32 v100, v100, v124
	v_mul_f32_e32 v101, v101, v124
	v_mul_f32_e32 v102, v102, v124
	v_mul_f32_e32 v103, v103, v124
	v_mul_f32_e32 v100, v100, v4
	v_mul_f32_e32 v101, v101, v5
	v_mul_f32_e32 v102, v102, v6
	v_mul_f32_e32 v103, v103, v7
	v_fma_f32 v100, v100, v20, v36
	v_fma_f32 v101, v101, v21, v37
	v_fma_f32 v102, v102, v22, v38
	v_fma_f32 v103, v103, v23, v39
	v_cvt_pk_bf16_f32 v130, v100, v101
	v_cvt_pk_bf16_f32 v131, v102, v103
	v_mul_f32_e32 v104, v104, v124
	v_mul_f32_e32 v105, v105, v124
	v_mul_f32_e32 v106, v106, v124
	v_mul_f32_e32 v107, v107, v124
	v_mul_f32_e32 v104, v104, v8
	v_mul_f32_e32 v105, v105, v9
	v_mul_f32_e32 v106, v106, v10
	v_mul_f32_e32 v107, v107, v11
	v_fma_f32 v104, v104, v24, v40
	v_fma_f32 v105, v105, v25, v41
	v_fma_f32 v106, v106, v26, v42
	v_fma_f32 v107, v107, v27, v43
	v_cvt_pk_bf16_f32 v132, v104, v105
	v_cvt_pk_bf16_f32 v133, v106, v107
	v_mul_f32_e32 v108, v108, v124
	v_mul_f32_e32 v109, v109, v124
	v_mul_f32_e32 v110, v110, v124
	v_mul_f32_e32 v111, v111, v124
	v_mul_f32_e32 v108, v108, v12
	v_mul_f32_e32 v109, v109, v13
	v_mul_f32_e32 v110, v110, v14
	v_mul_f32_e32 v111, v111, v15
	v_fma_f32 v108, v108, v28, v44
	v_fma_f32 v109, v109, v29, v45
	v_fma_f32 v110, v110, v30, v46
	v_fma_f32 v111, v111, v31, v47
	v_cvt_pk_bf16_f32 v134, v108, v109
	v_cvt_pk_bf16_f32 v135, v110, v111
	global_store_dwordx2 v119, v[128:129], s[10:11]
	global_store_dwordx2 v119, v[130:131], s[10:11] offset:512
	global_store_dwordx2 v119, v[132:133], s[10:11] offset:1024
	global_store_dwordx2 v119, v[134:135], s[10:11] offset:1536
.Lnrma_next:
	s_add_i32 s3, s3, 0x2000
	s_cmp_lt_u32 s3, 0x9000
	s_cbranch_scc1 .Lnrma_iter
	s_mov_b64 s[8:9], exec

; DI int otid() { int t = threadIdx.x & 255; asm volatile("" : "+v"(t)); return t; }
; DI int oidx(int i) { asm volatile("" : "+s"(i)); return i; }
; DN void norm_phase(const Params& p, int l, int which, bool from_input, bool skip_ctx) {
;   const int tid = otid(), lane = tid & 63;
;   const int wave = (VB() * 256 + tid) >> 6, nw = NVB() * 4;
;   const float* g = p.in[oidx(6) + which] + l * DM;
;   const float* MOD = (const float*)(p.ws + OFF_MOD);
;   bfr* H = (bfr*)(p.ws + OFF_HO);
;   for (int m0 = wave * 4; m0 < MR; m0 += nw * 4) {
;     f32x4v v[4][4];
;     float ss[4];
;     bool act[4];
;     const float* modp[4];
; #pragma unroll
;     for (int q = 0; q < 4; ++q) {
;       const int m = m0 + q;
;       const int b = m / TT, t = m - b * TT;
;       const bool isctx = t >= TL;
;       act[q] = !(isctx && skip_ctx);
;       const float* src = from_input ? in_row(p, b, t) : res_row(p, b, t);
;       modp[q] = MOD + (size_t)(l * 17 + (isctx ? 16 : b)) * 6144;
;       ss[q] = 0.f;
;       if (act[q]) {
; #pragma unroll
;         for (int i = 0; i < 4; ++i) {
;           v[q][i] = *(const f32x4v*)(src + i * 256 + lane * 4);
;           ss[q] += v[q][i].x * v[q][i].x + v[q][i].y * v[q][i].y + v[q][i].z * v[q][i].z + v[q][i].w * v[q][i].w;
;         }
;       } else {
; #pragma unroll
;         for (int i = 0; i < 4; ++i) v[q][i] = (f32x4v){0.f, 0.f, 0.f, 0.f};
;       }
;     }
; #pragma unroll
;     for (int q = 0; q < 4; ++q) {
;       if (!act[q]) continue;
;       const int m = m0 + q;
;       const float* shift = modp[q] + (which ? 3 : 0) * DM;
;       const float* scale = modp[q] + (which ? 4 : 1) * DM;
;       const float tot = wave_sum(ss[q]);
;       const float rstd = rsqrtf(tot * (1.f / DM) + 1e-6f);
; #pragma unroll
;       for (int i = 0; i < 4; ++i) {
;         const int k = i * 256 + lane * 4;
;         const f32x4v gg = *(const f32x4v*)(g + k), sc = *(const f32x4v*)(scale + k), sh = *(const f32x4v*)(shift + k);
;         const float o0 = (v[q][i].x * rstd * gg.x) * (1.f + sc.x) + sh.x;
;         const float o1 = (v[q][i].y * rstd * gg.y) * (1.f + sc.y) + sh.y;
;         const float o2 = (v[q][i].z * rstd * gg.z) * (1.f + sc.z) + sh.z;
;         const float o3 = (v[q][i].w * rstd * gg.w) * (1.f + sc.w) + sh.w;
;         uint2 pk; pk.x = pack2(o0, o1); pk.y = pack2(o2, o3);
;         *(uint2*)(H + (size_t)m * DM + k) = pk;
.LBB0_1193:
	s_or_b64 exec, exec, s[2:3]
	v_readfirstlane_b32 s2, v182
	v_mov_b32_e32 v0, v183
	s_lshr_b32 s2, s2, 8
	s_barrier
	v_readlane_b32 s2, v253, 13
	v_readlane_b32 s3, v252, 0
	v_readfirstlane_b32 s14, v182
	s_lshr_b32 s14, s14, 6
	s_lshl_b32 s3, s3, 3
	s_add_i32 s3, s3, s14
	s_lshl_b32 s3, s3, 2
	s_load_dwordx2 s[8:9], s[0:1], 0x38
	s_load_dwordx2 s[4:5], s[0:1], 0x108
	v_and_b32_e32 v112, 63, v182
	v_lshlrev_b32_e32 v116, 3, v112
	v_lshlrev_b32_e32 v112, 4, v112
	v_add_u32_e32 v113, 0x1000, v112
	v_add_u32_e32 v117, 0x800, v116
	v_add_u32_e32 v114, 0x2000, v112
	v_add_u32_e32 v118, 0x1000, v116
	v_add_u32_e32 v115, 0x3000, v112
	v_add_u32_e32 v119, 0x1800, v116
	s_lshl_b32 s14, s2, 12
	s_waitcnt lgkmcnt(0)
	s_add_u32 s8, s8, s14
	s_addc_u32 s9, s9, 0
	global_load_dwordx4 v[0:3], v112, s[8:9]
	global_load_dwordx4 v[4:7], v112, s[8:9] offset:1024
	global_load_dwordx4 v[8:11], v112, s[8:9] offset:2048
	global_load_dwordx4 v[12:15], v112, s[8:9] offset:3072
.Lnrmb_iter:
	s_mul_i32 s14, s3, 0xe39
	s_lshr_b32 s14, s14, 23
	s_mul_i32 s15, s14, 0x900
	s_sub_i32 s15, s3, s15
	s_cmpk_lt_i32 s15, 0x800
	s_cbranch_scc1 .Lnrmb_do
	s_cmp_eq_u32 s2, 1
	s_cbranch_scc1 .Lnrmb_next
.Lnrmb_do:
	s_cmpk_ge_i32 s15, 0x800
	s_cselect_b32 s98, 16, s14
	s_mul_i32 s99, s2, 17
	s_add_i32 s98, s98, s99
	s_mul_i32 s98, s98, 0x6000
	s_add_u32 s10, s4, 0x19f3000
	s_addc_u32 s11, s5, 0
	s_add_u32 s10, s10, s98
	s_addc_u32 s11, s11, 0
	s_add_u32 s12, s10, 0x1000
	s_addc_u32 s13, s11, 0
	global_load_dwordx4 v[32:35], v112, s[10:11]
	global_load_dwordx4 v[36:39], v112, s[10:11] offset:1024
	global_load_dwordx4 v[40:43], v112, s[10:11] offset:2048
	global_load_dwordx4 v[44:47], v112, s[10:11] offset:3072
	global_load_dwordx4 v[16:19], v112, s[12:13]
	global_load_dwordx4 v[20:23], v112, s[12:13] offset:1024
	global_load_dwordx4 v[24:27], v112, s[12:13] offset:2048
	global_load_dwordx4 v[28:31], v112, s[12:13] offset:3072
	s_cmpk_ge_i32 s15, 0x800
	s_movk_i32 s98, 0x100
	s_cselect_b32 s98, 0x108, s98
	s_load_dwordx2 s[8:9], s[0:1], s98
	s_lshl_b32 s99, s14, 11
	s_add_i32 s99, s99, s15
	s_lshl_b32 s14, s14, 8
	s_add_i32 s14, s14, s15
	s_addk_i32 s14, 0xf800
	s_cmpk_ge_i32 s15, 0x800
	s_cselect_b32 s99, s14, s99
	s_cselect_b32 s14, 0x1abc000, 0
	s_lshl_b32 s15, s99, 12
	s_waitcnt lgkmcnt(0)
	s_add_u32 s8, s8, s14
	s_addc_u32 s9, s9, 0
	s_add_u32 s8, s8, s15
	s_addc_u32 s9, s9, 0
	global_load_dwordx4 v[48:51], v112, s[8:9]
	global_load_dwordx4 v[52:55], v112, s[8:9] offset:1024
	global_load_dwordx4 v[56:59], v112, s[8:9] offset:2048
	global_load_dwordx4 v[60:63], v112, s[8:9] offset:3072
	global_load_dwordx4 v[64:67], v113, s[8:9]
	global_load_dwordx4 v[68:71], v113, s[8:9] offset:1024
	global_load_dwordx4 v[72:75], v113, s[8:9] offset:2048
	global_load_dwordx4 v[76:79], v113, s[8:9] offset:3072
	global_load_dwordx4 v[80:83], v114, s[8:9]
	global_load_dwordx4 v[84:87], v114, s[8:9] offset:1024
	global_load_dwordx4 v[88:91], v114, s[8:9] offset:2048
	global_load_dwordx4 v[92:95], v114, s[8:9] offset:3072
	global_load_dwordx4 v[96:99], v115, s[8:9]
	global_load_dwordx4 v[100:103], v115, s[8:9] offset:1024
	global_load_dwordx4 v[104:107], v115, s[8:9] offset:2048
	global_load_dwordx4 v[108:111], v115, s[8:9] offset:3072
	s_lshl_b32 s14, s3, 11
	s_add_u32 s10, s4, 0x2b7c100
	s_addc_u32 s11, s5, 0
	s_add_u32 s10, s10, s14
	s_addc_u32 s11, s11, 0
	s_waitcnt vmcnt(16)
	v_add_f32_e32 v16, 1.0, v16
	v_add_f32_e32 v17, 1.0, v17
	v_add_f32_e32 v18, 1.0, v18
	v_add_f32_e32 v19, 1.0, v19
	v_add_f32_e32 v20, 1.0, v20
	v_add_f32_e32 v21, 1.0, v21
	v_add_f32_e32 v22, 1.0, v22
	v_add_f32_e32 v23, 1.0, v23
	v_add_f32_e32 v24, 1.0, v24
	v_add_f32_e32 v25, 1.0, v25
	v_add_f32_e32 v26, 1.0, v26
	v_add_f32_e32 v27, 1.0, v27
	v_add_f32_e32 v28, 1.0, v28
	v_add_f32_e32 v29, 1.0, v29
	v_add_f32_e32 v30, 1.0, v30
	v_add_f32_e32 v31, 1.0, v31
	s_waitcnt vmcnt(12)
	v_mul_f32_e32 v120, v48, v48
	v_fmac_f32_e32 v120, v49, v49
	v_fmac_f32_e32 v120, v50, v50
	v_fmac_f32_e32 v120, v51, v51
	v_fmac_f32_e32 v120, v52, v52
	v_fmac_f32_e32 v120, v53, v53
	v_fmac_f32_e32 v120, v54, v54
	v_fmac_f32_e32 v120, v55, v55
	v_fmac_f32_e32 v120, v56, v56
	v_fmac_f32_e32 v120, v57, v57
	v_fmac_f32_e32 v120, v58, v58
	v_fmac_f32_e32 v120, v59, v59
	v_fmac_f32_e32 v120, v60, v60
	v_fmac_f32_e32 v120, v61, v61
	v_fmac_f32_e32 v120, v62, v62
	v_fmac_f32_e32 v120, v63, v63
	s_nop 1
	v_add_f32_dpp v120, v120, v120 quad_perm:[1,0,3,2] row_mask:0xf bank_mask:0xf bound_ctrl:1
	s_nop 1
	v_add_f32_dpp v120, v120, v120 quad_perm:[2,3,0,1] row_mask:0xf bank_mask:0xf bound_ctrl:1
	s_nop 1
	v_add_f32_dpp v120, v120, v120 row_half_mirror row_mask:0xf bank_mask:0xf bound_ctrl:1
	s_nop 1
	v_add_f32_dpp v120, v120, v120 row_mirror row_mask:0xf bank_mask:0xf bound_ctrl:1
	s_nop 1
	v_readlane_b32 s14, v120, 0
	v_readlane_b32 s15, v120, 16
	v_readlane_b32 s98, v120, 32
	v_readlane_b32 s99, v120, 48
	s_nop 1
	v_mov_b32_e32 v124, s14
	v_mov_b32_e32 v125, s98
	v_add_f32_e32 v124, s15, v124
	v_add_f32_e32 v125, s99, v125
	v_add_f32_e32 v124, v124, v125
	v_mul_f32_e32 v124, 0x3a800000, v124
	v_add_f32_e32 v124, 0x358637bd, v124
	v_rsq_f32_e32 v124, v124
	s_nop 0
	v_mul_f32_e32 v48, v48, v124
	v_mul_f32_e32 v49, v49, v124
	v_mul_f32_e32 v50, v50, v124
	v_mul_f32_e32 v51, v51, v124
	v_mul_f32_e32 v48, v48, v0
	v_mul_f32_e32 v49, v49, v1
	v_mul_f32_e32 v50, v50, v2
	v_mul_f32_e32 v51, v51, v3
	v_fma_f32 v48, v48, v16, v32
	v_fma_f32 v49, v49, v17, v33
	v_fma_f32 v50, v50, v18, v34
	v_fma_f32 v51, v51, v19, v35
	v_cvt_pk_bf16_f32 v128, v48, v49
	v_cvt_pk_bf16_f32 v129, v50, v51
	v_mul_f32_e32 v52, v52, v124
	v_mul_f32_e32 v53, v53, v124
; DI unsigned pack2(float a, float b) { unsigned r; asm volatile("v_cvt_pk_bf16_f32 %0, %1, %2" : "=v"(r) : "v"(a), "v"(b)); return r; }
; DN void norm_phase(const Params& p, int l, int which, bool from_input, bool skip_ctx) {
;     ...
; #pragma unroll
;     for (int q = 0; q < 4; ++q) {
;       if (!act[q]) continue;
;       const int m = m0 + q;
;       const float* shift = modp[q] + (which ? 3 : 0) * DM;
;       const float* scale = modp[q] + (which ? 4 : 1) * DM;
;       const float tot = wave_sum(ss[q]);
;       const float rstd = rsqrtf(tot * (1.f / DM) + 1e-6f);
; #pragma unroll
;       for (int i = 0; i < 4; ++i) {
;         const int k = i * 256 + lane * 4;
;         const f32x4v gg = *(const f32x4v*)(g + k), sc = *(const f32x4v*)(scale + k), sh = *(const f32x4v*)(shift + k);
;         const float o0 = (v[q][i].x * rstd * gg.x) * (1.f + sc.x) + sh.x;
;         const float o1 = (v[q][i].y * rstd * gg.y) * (1.f + sc.y) + sh.y;
;         const float o2 = (v[q][i].z * rstd * gg.z) * (1.f + sc.z) + sh.z;
;         const float o3 = (v[q][i].w * rstd * gg.w) * (1.f + sc.w) + sh.w;
;         uint2 pk; pk.x = pack2(o0, o1); pk.y = pack2(o2, o3);
;         *(uint2*)(H + (size_t)m * DM + k) = pk;
;       }
	v_mul_f32_e32 v54, v54, v124
	v_mul_f32_e32 v55, v55, v124
	v_mul_f32_e32 v52, v52, v4
	v_mul_f32_e32 v53, v53, v5
	v_mul_f32_e32 v54, v54, v6
	v_mul_f32_e32 v55, v55, v7
	v_fma_f32 v52, v52, v20, v36
	v_fma_f32 v53, v53, v21, v37
	v_fma_f32 v54, v54, v22, v38
	v_fma_f32 v55, v55, v23, v39
	v_cvt_pk_bf16_f32 v130, v52, v53
	v_cvt_pk_bf16_f32 v131, v54, v55
	v_mul_f32_e32 v56, v56, v124
	v_mul_f32_e32 v57, v57, v124
	v_mul_f32_e32 v58, v58, v124
	v_mul_f32_e32 v59, v59, v124
	v_mul_f32_e32 v56, v56, v8
	v_mul_f32_e32 v57, v57, v9
	v_mul_f32_e32 v58, v58, v10
	v_mul_f32_e32 v59, v59, v11
	v_fma_f32 v56, v56, v24, v40
	v_fma_f32 v57, v57, v25, v41
	v_fma_f32 v58, v58, v26, v42
	v_fma_f32 v59, v59, v27, v43
	v_cvt_pk_bf16_f32 v132, v56, v57
	v_cvt_pk_bf16_f32 v133, v58, v59
	v_mul_f32_e32 v60, v60, v124
	v_mul_f32_e32 v61, v61, v124
	v_mul_f32_e32 v62, v62, v124
	v_mul_f32_e32 v63, v63, v124
	v_mul_f32_e32 v60, v60, v12
	v_mul_f32_e32 v61, v61, v13
	v_mul_f32_e32 v62, v62, v14
	v_mul_f32_e32 v63, v63, v15
	v_fma_f32 v60, v60, v28, v44
	v_fma_f32 v61, v61, v29, v45
	v_fma_f32 v62, v62, v30, v46
	v_fma_f32 v63, v63, v31, v47
	v_cvt_pk_bf16_f32 v134, v60, v61
	v_cvt_pk_bf16_f32 v135, v62, v63
	global_store_dwordx2 v116, v[128:129], s[10:11]
	global_store_dwordx2 v116, v[130:131], s[10:11] offset:512
	global_store_dwordx2 v116, v[132:133], s[10:11] offset:1024
	global_store_dwordx2 v116, v[134:135], s[10:11] offset:1536
	s_waitcnt vmcnt(12)
	v_mul_f32_e32 v121, v64, v64
	v_fmac_f32_e32 v121, v65, v65
	v_fmac_f32_e32 v121, v66, v66
	v_fmac_f32_e32 v121, v67, v67
	v_fmac_f32_e32 v121, v68, v68
	v_fmac_f32_e32 v121, v69, v69
	v_fmac_f32_e32 v121, v70, v70
	v_fmac_f32_e32 v121, v71, v71
	v_fmac_f32_e32 v121, v72, v72
	v_fmac_f32_e32 v121, v73, v73
	v_fmac_f32_e32 v121, v74, v74
	v_fmac_f32_e32 v121, v75, v75
	v_fmac_f32_e32 v121, v76, v76
	v_fmac_f32_e32 v121, v77, v77
	v_fmac_f32_e32 v121, v78, v78
	v_fmac_f32_e32 v121, v79, v79
	s_nop 1
	v_add_f32_dpp v121, v121, v121 quad_perm:[1,0,3,2] row_mask:0xf bank_mask:0xf bound_ctrl:1
	s_nop 1
	v_add_f32_dpp v121, v121, v121 quad_perm:[2,3,0,1] row_mask:0xf bank_mask:0xf bound_ctrl:1
	s_nop 1
	v_add_f32_dpp v121, v121, v121 row_half_mirror row_mask:0xf bank_mask:0xf bound_ctrl:1
	s_nop 1
	v_add_f32_dpp v121, v121, v121 row_mirror row_mask:0xf bank_mask:0xf bound_ctrl:1
	s_nop 1
	v_readlane_b32 s14, v121, 0
	v_readlane_b32 s15, v121, 16
	v_readlane_b32 s98, v121, 32
	v_readlane_b32 s99, v121, 48
	s_nop 1
	v_mov_b32_e32 v124, s14
	v_mov_b32_e32 v125, s98
	v_add_f32_e32 v124, s15, v124
	v_add_f32_e32 v125, s99, v125
	v_add_f32_e32 v124, v124, v125
	v_mul_f32_e32 v124, 0x3a800000, v124
	v_add_f32_e32 v124, 0x358637bd, v124
	v_rsq_f32_e32 v124, v124
	s_nop 0
	v_mul_f32_e32 v64, v64, v124
	v_mul_f32_e32 v65, v65, v124
	v_mul_f32_e32 v66, v66, v124
	v_mul_f32_e32 v67, v67, v124
	v_mul_f32_e32 v64, v64, v0
	v_mul_f32_e32 v65, v65, v1
	v_mul_f32_e32 v66, v66, v2
	v_mul_f32_e32 v67, v67, v3
	v_fma_f32 v64, v64, v16, v32
	v_fma_f32 v65, v65, v17, v33
	v_fma_f32 v66, v66, v18, v34
	v_fma_f32 v67, v67, v19, v35
	v_cvt_pk_bf16_f32 v128, v64, v65
	v_cvt_pk_bf16_f32 v129, v66, v67
	v_mul_f32_e32 v68, v68, v124
	v_mul_f32_e32 v69, v69, v124
	v_mul_f32_e32 v70, v70, v124
	v_mul_f32_e32 v71, v71, v124
	v_mul_f32_e32 v68, v68, v4
	v_mul_f32_e32 v69, v69, v5
	v_mul_f32_e32 v70, v70, v6
	v_mul_f32_e32 v71, v71, v7
	v_fma_f32 v68, v68, v20, v36
	v_fma_f32 v69, v69, v21, v37
	v_fma_f32 v70, v70, v22, v38
	v_fma_f32 v71, v71, v23, v39
	v_cvt_pk_bf16_f32 v130, v68, v69
	v_cvt_pk_bf16_f32 v131, v70, v71
	v_mul_f32_e32 v72, v72, v124
	v_mul_f32_e32 v73, v73, v124
	v_mul_f32_e32 v74, v74, v124
	v_mul_f32_e32 v75, v75, v124
	v_mul_f32_e32 v72, v72, v8
	v_mul_f32_e32 v73, v73, v9
	v_mul_f32_e32 v74, v74, v10
	v_mul_f32_e32 v75, v75, v11
	v_fma_f32 v72, v72, v24, v40
	v_fma_f32 v73, v73, v25, v41
	v_fma_f32 v74, v74, v26, v42
	v_fma_f32 v75, v75, v27, v43
	v_cvt_pk_bf16_f32 v132, v72, v73
	v_cvt_pk_bf16_f32 v133, v74, v75
	v_mul_f32_e32 v76, v76, v124
	v_mul_f32_e32 v77, v77, v124
	v_mul_f32_e32 v78, v78, v124
	v_mul_f32_e32 v79, v79, v124
	v_mul_f32_e32 v76, v76, v12
	v_mul_f32_e32 v77, v77, v13
	v_mul_f32_e32 v78, v78, v14
	v_mul_f32_e32 v79, v79, v15
	v_fma_f32 v76, v76, v28, v44
	v_fma_f32 v77, v77, v29, v45
	v_fma_f32 v78, v78, v30, v46
	v_fma_f32 v79, v79, v31, v47
	v_cvt_pk_bf16_f32 v134, v76, v77
	v_cvt_pk_bf16_f32 v135, v78, v79
	global_store_dwordx2 v117, v[128:129], s[10:11]
	global_store_dwordx2 v117, v[130:131], s[10:11] offset:512
	global_store_dwordx2 v117, v[132:133], s[10:11] offset:1024
	global_store_dwordx2 v117, v[134:135], s[10:11] offset:1536
	s_waitcnt vmcnt(12)
; DI unsigned pack2(float a, float b) { unsigned r; asm volatile("v_cvt_pk_bf16_f32 %0, %1, %2" : "=v"(r) : "v"(a), "v"(b)); return r; }
; DN void norm_phase(const Params& p, int l, int which, bool from_input, bool skip_ctx) {
;     ...
; #pragma unroll
;     for (int q = 0; q < 4; ++q) {
;       if (!act[q]) continue;
;       const int m = m0 + q;
;       const float* shift = modp[q] + (which ? 3 : 0) * DM;
;       const float* scale = modp[q] + (which ? 4 : 1) * DM;
;       const float tot = wave_sum(ss[q]);
;       const float rstd = rsqrtf(tot * (1.f / DM) + 1e-6f);
; #pragma unroll
;       for (int i = 0; i < 4; ++i) {
;         const int k = i * 256 + lane * 4;
;         const f32x4v gg = *(const f32x4v*)(g + k), sc = *(const f32x4v*)(scale + k), sh = *(const f32x4v*)(shift + k);
;         const float o0 = (v[q][i].x * rstd * gg.x) * (1.f + sc.x) + sh.x;
;         const float o1 = (v[q][i].y * rstd * gg.y) * (1.f + sc.y) + sh.y;
;         const float o2 = (v[q][i].z * rstd * gg.z) * (1.f + sc.z) + sh.z;
;         const float o3 = (v[q][i].w * rstd * gg.w) * (1.f + sc.w) + sh.w;
;         uint2 pk; pk.x = pack2(o0, o1); pk.y = pack2(o2, o3);
;         *(uint2*)(H + (size_t)m * DM + k) = pk;
;       }
;     }
;   }
	v_mul_f32_e32 v122, v80, v80
	v_fmac_f32_e32 v122, v81, v81
	v_fmac_f32_e32 v122, v82, v82
	v_fmac_f32_e32 v122, v83, v83
	v_fmac_f32_e32 v122, v84, v84
	v_fmac_f32_e32 v122, v85, v85
	v_fmac_f32_e32 v122, v86, v86
	v_fmac_f32_e32 v122, v87, v87
	v_fmac_f32_e32 v122, v88, v88
	v_fmac_f32_e32 v122, v89, v89
	v_fmac_f32_e32 v122, v90, v90
	v_fmac_f32_e32 v122, v91, v91
	v_fmac_f32_e32 v122, v92, v92
	v_fmac_f32_e32 v122, v93, v93
	v_fmac_f32_e32 v122, v94, v94
	v_fmac_f32_e32 v122, v95, v95
	s_nop 1
	v_add_f32_dpp v122, v122, v122 quad_perm:[1,0,3,2] row_mask:0xf bank_mask:0xf bound_ctrl:1
	s_nop 1
	v_add_f32_dpp v122, v122, v122 quad_perm:[2,3,0,1] row_mask:0xf bank_mask:0xf bound_ctrl:1
	s_nop 1
	v_add_f32_dpp v122, v122, v122 row_half_mirror row_mask:0xf bank_mask:0xf bound_ctrl:1
	s_nop 1
	v_add_f32_dpp v122, v122, v122 row_mirror row_mask:0xf bank_mask:0xf bound_ctrl:1
	s_nop 1
	v_readlane_b32 s14, v122, 0
	v_readlane_b32 s15, v122, 16
	v_readlane_b32 s98, v122, 32
	v_readlane_b32 s99, v122, 48
	s_nop 1
	v_mov_b32_e32 v124, s14
	v_mov_b32_e32 v125, s98
	v_add_f32_e32 v124, s15, v124
	v_add_f32_e32 v125, s99, v125
	v_add_f32_e32 v124, v124, v125
	v_mul_f32_e32 v124, 0x3a800000, v124
	v_add_f32_e32 v124, 0x358637bd, v124
	v_rsq_f32_e32 v124, v124
	s_nop 0
	v_mul_f32_e32 v80, v80, v124
	v_mul_f32_e32 v81, v81, v124
	v_mul_f32_e32 v82, v82, v124
	v_mul_f32_e32 v83, v83, v124
	v_mul_f32_e32 v80, v80, v0
	v_mul_f32_e32 v81, v81, v1
	v_mul_f32_e32 v82, v82, v2
	v_mul_f32_e32 v83, v83, v3
	v_fma_f32 v80, v80, v16, v32
	v_fma_f32 v81, v81, v17, v33
	v_fma_f32 v82, v82, v18, v34
	v_fma_f32 v83, v83, v19, v35
	v_cvt_pk_bf16_f32 v128, v80, v81
	v_cvt_pk_bf16_f32 v129, v82, v83
	v_mul_f32_e32 v84, v84, v124
	v_mul_f32_e32 v85, v85, v124
	v_mul_f32_e32 v86, v86, v124
	v_mul_f32_e32 v87, v87, v124
	v_mul_f32_e32 v84, v84, v4
	v_mul_f32_e32 v85, v85, v5
	v_mul_f32_e32 v86, v86, v6
	v_mul_f32_e32 v87, v87, v7
	v_fma_f32 v84, v84, v20, v36
	v_fma_f32 v85, v85, v21, v37
	v_fma_f32 v86, v86, v22, v38
	v_fma_f32 v87, v87, v23, v39
	v_cvt_pk_bf16_f32 v130, v84, v85
	v_cvt_pk_bf16_f32 v131, v86, v87
	v_mul_f32_e32 v88, v88, v124
	v_mul_f32_e32 v89, v89, v124
	v_mul_f32_e32 v90, v90, v124
	v_mul_f32_e32 v91, v91, v124
	v_mul_f32_e32 v88, v88, v8
	v_mul_f32_e32 v89, v89, v9
	v_mul_f32_e32 v90, v90, v10
	v_mul_f32_e32 v91, v91, v11
	v_fma_f32 v88, v88, v24, v40
	v_fma_f32 v89, v89, v25, v41
	v_fma_f32 v90, v90, v26, v42
	v_fma_f32 v91, v91, v27, v43
	v_cvt_pk_bf16_f32 v132, v88, v89
	v_cvt_pk_bf16_f32 v133, v90, v91
	v_mul_f32_e32 v92, v92, v124
	v_mul_f32_e32 v93, v93, v124
	v_mul_f32_e32 v94, v94, v124
	v_mul_f32_e32 v95, v95, v124
	v_mul_f32_e32 v92, v92, v12
	v_mul_f32_e32 v93, v93, v13
	v_mul_f32_e32 v94, v94, v14
	v_mul_f32_e32 v95, v95, v15
	v_fma_f32 v92, v92, v28, v44
	v_fma_f32 v93, v93, v29, v45
	v_fma_f32 v94, v94, v30, v46
	v_fma_f32 v95, v95, v31, v47
	v_cvt_pk_bf16_f32 v134, v92, v93
	v_cvt_pk_bf16_f32 v135, v94, v95
	global_store_dwordx2 v118, v[128:129], s[10:11]
	global_store_dwordx2 v118, v[130:131], s[10:11] offset:512
	global_store_dwordx2 v118, v[132:133], s[10:11] offset:1024
	global_store_dwordx2 v118, v[134:135], s[10:11] offset:1536
	s_waitcnt vmcnt(12)
	v_mul_f32_e32 v123, v96, v96
	v_fmac_f32_e32 v123, v97, v97
	v_fmac_f32_e32 v123, v98, v98
	v_fmac_f32_e32 v123, v99, v99
	v_fmac_f32_e32 v123, v100, v100
	v_fmac_f32_e32 v123, v101, v101
	v_fmac_f32_e32 v123, v102, v102
	v_fmac_f32_e32 v123, v103, v103
	v_fmac_f32_e32 v123, v104, v104
	v_fmac_f32_e32 v123, v105, v105
	v_fmac_f32_e32 v123, v106, v106
	v_fmac_f32_e32 v123, v107, v107
	v_fmac_f32_e32 v123, v108, v108
	v_fmac_f32_e32 v123, v109, v109
	v_fmac_f32_e32 v123, v110, v110
	v_fmac_f32_e32 v123, v111, v111
	s_nop 1
	v_add_f32_dpp v123, v123, v123 quad_perm:[1,0,3,2] row_mask:0xf bank_mask:0xf bound_ctrl:1
	s_nop 1
	v_add_f32_dpp v123, v123, v123 quad_perm:[2,3,0,1] row_mask:0xf bank_mask:0xf bound_ctrl:1
	s_nop 1
	v_add_f32_dpp v123, v123, v123 row_half_mirror row_mask:0xf bank_mask:0xf bound_ctrl:1
	s_nop 1
	v_add_f32_dpp v123, v123, v123 row_mirror row_mask:0xf bank_mask:0xf bound_ctrl:1
	s_nop 1
	v_readlane_b32 s14, v123, 0
	v_readlane_b32 s15, v123, 16
	v_readlane_b32 s98, v123, 32
	v_readlane_b32 s99, v123, 48
	s_nop 1
	v_mov_b32_e32 v124, s14
	v_mov_b32_e32 v125, s98
	v_add_f32_e32 v124, s15, v124
	v_add_f32_e32 v125, s99, v125
	v_add_f32_e32 v124, v124, v125
	v_mul_f32_e32 v124, 0x3a800000, v124
	v_add_f32_e32 v124, 0x358637bd, v124
	v_rsq_f32_e32 v124, v124
	s_nop 0
	v_mul_f32_e32 v96, v96, v124
	v_mul_f32_e32 v97, v97, v124
	v_mul_f32_e32 v98, v98, v124
	v_mul_f32_e32 v99, v99, v124
	v_mul_f32_e32 v96, v96, v0
	v_mul_f32_e32 v97, v97, v1
	v_mul_f32_e32 v98, v98, v2
	v_mul_f32_e32 v99, v99, v3
	v_fma_f32 v96, v96, v16, v32
	v_fma_f32 v97, v97, v17, v33
	v_fma_f32 v98, v98, v18, v34
	v_fma_f32 v99, v99, v19, v35
	v_cvt_pk_bf16_f32 v128, v96, v97
	v_cvt_pk_bf16_f32 v129, v98, v99
	v_mul_f32_e32 v100, v100, v124
	v_mul_f32_e32 v101, v101, v124
	v_mul_f32_e32 v102, v102, v124
	v_mul_f32_e32 v103, v103, v124
	v_mul_f32_e32 v100, v100, v4
	v_mul_f32_e32 v101, v101, v5
	v_mul_f32_e32 v102, v102, v6
	v_mul_f32_e32 v103, v103, v7
	v_fma_f32 v100, v100, v20, v36
	v_fma_f32 v101, v101, v21, v37
	v_fma_f32 v102, v102, v22, v38
	v_fma_f32 v103, v103, v23, v39
	v_cvt_pk_bf16_f32 v130, v100, v101
	v_cvt_pk_bf16_f32 v131, v102, v103
	v_mul_f32_e32 v104, v104, v124
	v_mul_f32_e32 v105, v105, v124
	v_mul_f32_e32 v106, v106, v124
	v_mul_f32_e32 v107, v107, v124
	v_mul_f32_e32 v104, v104, v8
	v_mul_f32_e32 v105, v105, v9
	v_mul_f32_e32 v106, v106, v10
	v_mul_f32_e32 v107, v107, v11
	v_fma_f32 v104, v104, v24, v40
	v_fma_f32 v105, v105, v25, v41
	v_fma_f32 v106, v106, v26, v42
	v_fma_f32 v107, v107, v27, v43
	v_cvt_pk_bf16_f32 v132, v104, v105
	v_cvt_pk_bf16_f32 v133, v106, v107
	v_mul_f32_e32 v108, v108, v124
	v_mul_f32_e32 v109, v109, v124
	v_mul_f32_e32 v110, v110, v124
	v_mul_f32_e32 v111, v111, v124
	v_mul_f32_e32 v108, v108, v12
	v_mul_f32_e32 v109, v109, v13
	v_mul_f32_e32 v110, v110, v14
	v_mul_f32_e32 v111, v111, v15
	v_fma_f32 v108, v108, v28, v44
	v_fma_f32 v109, v109, v29, v45
	v_fma_f32 v110, v110, v30, v46
	v_fma_f32 v111, v111, v31, v47
	v_cvt_pk_bf16_f32 v134, v108, v109
	v_cvt_pk_bf16_f32 v135, v110, v111
	global_store_dwordx2 v119, v[128:129], s[10:11]
	global_store_dwordx2 v119, v[130:131], s[10:11] offset:512
	global_store_dwordx2 v119, v[132:133], s[10:11] offset:1024
	global_store_dwordx2 v119, v[134:135], s[10:11] offset:1536
.Lnrmb_next:
	s_add_i32 s3, s3, 0x2000
	s_cmp_lt_u32 s3, 0x9000
	s_cbranch_scc1 .Lnrmb_iter
	s_mov_b64 s[4:5], exec
